# layer-0 up-GEMM: fifth latent tile of the ctx-tile workgroups moved to workgroups that had five
# speedup vs baseline: 1.0426x; 1.0005x over previous
.LBB0_776:
	s_add_i32 s43, s43, 1
	s_mul_i32 s6, s43, s91
	s_mul_hi_u32 s7, s43, s66
	s_add_i32 s7, s7, s6
	s_mul_i32 s6, s43, s66
	s_add_u32 s20, s6, s62
	s_addc_u32 s21, s7, s90
	v_readlane_b32 s22, v254, 47
	s_nop 3
	s_cmp_lg_u32 s22, 0
	s_cbranch_scc1 .Lp8b_done
	s_sub_i32 s22, s62, 0x80
	s_cmp_lt_u32 s22, 88
	s_cbranch_scc0 .Lp8b_done
	s_cmp_lt_u32 s22, 44
	s_cbranch_scc0 .Lp8b_b
	s_cmp_eq_u32 s43, 4
	s_cselect_b32 s20, 0x7fffffff, s20
	s_branch .Lp8b_done
.Lp8b_b:
	s_add_i32 s22, s62, 0x3d4
	s_cmp_eq_u32 s43, 5
	s_cselect_b32 s20, s22, s20
	s_cselect_b32 s21, 0, s21
.Lp8b_done:
	v_mov_b64_e32 v[0:1], 0x580
	v_cmp_lt_i64_e64 s[6:7], s[20:21], v[0:1]
	v_mov_b64_e32 v[0:1], 0x57f
	v_cmp_gt_i64_e32 vcc, s[20:21], v[0:1]
	s_cbranch_vccnz .LBB0_778
	s_ashr_i32 s16, s20, 31
	s_lshr_b32 s16, s16, 29
	s_add_i32 s16, s20, s16
	s_ashr_i32 s17, s16, 3
	s_and_b32 s16, s16, -8
	s_sub_i32 s16, s20, s16
	s_cmp_lt_i32 s16, 0
	s_cselect_b32 s18, s71, 0xb0
	s_mul_i32 s16, s16, s18
	s_add_i32 s16, s16, s17
	s_mul_hi_i32 s17, s16, 0x2e8ba2e9
	s_lshr_b32 s18, s17, 31
	s_ashr_i32 s17, s17, 4
	s_add_i32 s17, s17, s18
	s_lshl_b32 s18, s17, 2
	s_sub_i32 s19, 64, s18
	s_min_i32 s19, s19, 4
	s_abs_i32 s20, s19
	v_cvt_f32_u32_e32 v0, s20
	s_sub_i32 s22, 0, s20
	s_mulk_i32 s17, 0x58
	s_sub_i32 s17, s16, s17
	v_rcp_iflag_f32_e32 v0, v0
	s_abs_i32 s16, s17
	s_xor_b32 s21, s17, s19
	s_ashr_i32 s21, s21, 31
	v_mul_f32_e32 v0, 0x4f7ffffe, v0
	v_cvt_u32_f32_e32 v0, v0
	s_nop 0
	v_readfirstlane_b32 s23, v0
	s_mul_i32 s22, s22, s23
	s_mul_hi_u32 s22, s23, s22
	s_add_i32 s23, s23, s22
	s_mul_hi_u32 s22, s16, s23
	s_mul_i32 s23, s22, s20
	s_sub_i32 s16, s16, s23
	s_add_i32 s28, s22, 1
	s_sub_i32 s23, s16, s20
	s_cmp_ge_u32 s16, s20
	s_cselect_b32 s22, s28, s22
	s_cselect_b32 s16, s23, s16
	s_add_i32 s23, s22, 1
	s_cmp_ge_u32 s16, s20
	s_cselect_b32 s16, s23, s22
	s_xor_b32 s16, s16, s21
	s_sub_i32 s16, s16, s21
	s_mul_i32 s19, s16, s19
	s_sub_i32 s17, s17, s19
	s_add_i32 s18, s18, s17
